# attention loop-top K/V tile loads in SGPR-base form (addresses advanced on SALU, 4 fewer VALU per tile) on top of v25
# speedup vs baseline: 1.0111x; 1.0111x over previous
; #define LAS __attribute__((address_space(3)))
; __device__ __forceinline__ int otid() { int t = threadIdx.x; asm volatile("" : "+v"(t)); return t; }
; __device__ __forceinline__ int obid() { int t = blockIdx.x; asm volatile("" : "+s"(t)); return t; }
; __device__ __forceinline__ void phase_attn(const Params& p, int S, int lgS, int B, int* counter, LAS unsigned char* lds) {
;     unsigned char* const ws_ = ows(p);
;     const int tid = otid(), lane = tid & 63, wid = __builtin_amdgcn_readfirstlane(tid >> 6), r32 = lane & 31, hi = lane >> 5;
;     const bf16_t* Z = (const bf16_t*)(ws_ + WS_BIG + BG_Z); const bf16_t* VT = (const bf16_t*)(ws_ + WS_BIG + BG_VT); bf16_t* YC = (bf16_t*)(ws_ + WS_YC);
;     constexpr int KB = 128 * 72 * 2, BUFB = KB + 64 * 136 * 2;
;     const int nqt = S >> 8, lgq = lgS - 8, nunits = B * 8 * nqt, NT = S >> 7;
;     LAS float* wsf = (LAS float*)(lds + 2 * BUFB + wid * 256);
;     const int skey = tid >> 3, spc = tid & 7;
;     const int kdst = (skey * 72 + spc * 8) * 2, vdst = KB + (skey * 136 + spc * 8) * 2;
;     const int klane = (r32 * 72 + 8 * hi) * 2, vlane = (r32 * 136 + 4 * hi) * 2;
;     const int G_ = (int)gridDim.x, bid_ = obid(), nscan = B * 16, per = nunits / G_;
;     const bool deal = (nunits % G_ == 0) && (2 * nscan <= G_) && (per >= 2);
;     const int nmine = !deal ? ((bid_ < nunits) ? (nunits - bid_ + G_ - 1) / G_ : 0) : (bid_ < nscan ? per - 1 : (bid_ < 2 * nscan ? per + 1 : per));
;     for (int ui = 0; ui < nmine; ++ui) {
;         const int unit = (deal && ui == per) ? (bid_ - nscan) + G_ * (per - 1) : bid_ + ui * G_;
;         const int hq4 = unit & 3, qt = (unit >> 2) & (nqt - 1), bk = unit >> (2 + lgq), kvh = bk & 1, b = bk >> 1, qh = kvh * 4 + hq4;
;         const size_t rowq = (size_t)b * S + qt * 256 + wid * 32 + r32;
;         bf16x8 qr[4];
; #pragma unroll
;         for (int d0 = 0; d0 < 4; ++d0) qr[d0] = *(const bf16x8*)(Z + rowq * 2048 + qh * 64 + d0 * 16 + hi * 8);
;         const bf16_t* ksrc = Z + ((size_t)b * S + skey) * 2048 + 512 + kvh * 64 + spc * 8;
;         const bf16_t* vsrc = VT + (((size_t)(b * 128 + kvh * 64 + skey)) << lgS) + spc * 8;
;         u32x4 kreg0 = *(const u32x4*)ksrc, kreg1 = *(const u32x4*)(ksrc + (size_t)64 * 2048), vreg0 = *(const u32x4*)vsrc, vreg1 = *(const u32x4*)(vsrc + 64);
.LBB0_725:
	s_cmp_lt_i32 s1, 1
	s_cbranch_scc1 .LBB0_741
	s_ashr_i32 s4, s2, 6
	s_add_u32 s8, s6, 0x13800000
	s_addc_u32 s9, s7, 0
	s_lshl_b32 s2, s4, 8
	s_add_i32 s2, s2, 0
	v_lshlrev_b32_e32 v2, 3, v0
	v_bfe_u32 v3, v0, 5, 1
	s_add_i32 s10, s2, 0x11800
	v_ashrrev_i32_e32 v146, 3, v0
	v_and_b32_e32 v2, 56, v2
	s_movk_i32 s2, 0x48
	v_mad_u64_u32 v[4:5], s[2:3], v146, s2, v[2:3]
	v_readlane_b32 s2, v251, 30
	v_readlane_b32 s3, v251, 31
	v_and_b32_e32 v144, 31, v0
	v_lshlrev_b32_e32 v5, 6, v146
	v_readlane_b32 s3, v251, 39
	v_lshlrev_b32_e32 v145, 1, v4
	v_lshlrev_b32_e32 v149, 4, v0
	v_and_b32_e32 v149, 0x60, v149
	v_lshlrev_b32_e32 v5, 3, v0
	v_and_b32_e32 v5, 8, v5
	v_add_u32_e32 v149, v149, v5
	v_mul_u32_u24_e32 v5, 0x110, v146
	v_add_u32_e32 v149, v149, v5
	v_add_u32_e32 v149, 0x4800, v149
	v_mul_u32_u24_e32 v4, 0x48, v144
	v_lshlrev_b32_e32 v148, 3, v3
	s_sub_i32 s2, s0, s2
	s_mul_i32 s3, s3, s92
	v_lshlrev_b32_e32 v200, 1, v2
	v_and_b32_e32 v1, 63, v0
	v_add_lshl_u32 v198, v148, v4, 1
	s_add_i32 s2, s2, s3
	s_lshl_b32 s3, s4, 5
	v_lshl_add_u64 v[4:5], s[6:7], 0, v[200:201]
	s_mov_b64 s[4:5], 0x27800000
	v_lshl_add_u64 v[150:151], v[4:5], 0, s[4:5]
	v_lshlrev_b32_e32 v4, 2, v1
	v_and_b32_e32 v0, 7, v0
	v_xor_b32_e32 v209, 0x80, v4
	v_cmp_gt_u32_e64 s[4:5], 32, v1
	v_lshlrev_b32_e32 v1, 4, v3
	v_lshlrev_b32_e32 v4, 12, v3
	v_lshlrev_b32_e32 v200, 4, v0
	v_mul_u32_u24_e32 v199, 0x110, v144
	v_lshl_add_u32 v219, v144, 2, s10
	v_add_u32_e32 v222, s10, v1
	v_add_u32_e32 v5, 0, v148
	v_or_b32_e32 v6, 0x400, v4
	v_or_b32_e32 v8, 0x800, v4
	v_or_b32_e32 v10, 0xc00, v4
	v_or_b32_e32 v12, 0x2000, v4
	v_or_b32_e32 v14, 0x2400, v4
	v_or_b32_e32 v16, 0x2800, v4
	v_or_b32_e32 v18, 0x2c00, v4
	v_or_b32_e32 v20, 0x4000, v4
	v_or_b32_e32 v22, 0x4400, v4
	v_or_b32_e32 v24, 0x4800, v4
	v_or_b32_e32 v26, 0x4c00, v4
	v_or_b32_e32 v28, 0x6000, v4
	v_or_b32_e32 v30, 0x6400, v4
	v_or_b32_e32 v32, 0x6800, v4
	v_or_b32_e32 v34, 0x6c00, v4
	v_lshl_add_u64 v[0:1], s[6:7], 0, v[200:201]
	s_mov_b64 s[10:11], 0x13940400
	s_ashr_i32 s14, s3, 31
	v_ashrrev_i32_e32 v147, 31, v146
	v_lshl_add_u64 v[152:153], v[0:1], 0, s[10:11]
	s_mov_b32 s15, 0
	v_lshl_add_u32 v223, v148, 1, v199
	v_lshlrev_b32_e32 v200, 1, v144
	v_lshlrev_b32_e32 v154, 1, v4
	v_lshlrev_b32_e32 v156, 1, v6
	v_lshlrev_b32_e32 v158, 1, v8
	v_lshlrev_b32_e32 v160, 1, v10
	v_lshlrev_b32_e32 v162, 1, v12
	v_lshlrev_b32_e32 v164, 1, v14
	v_lshlrev_b32_e32 v166, 1, v16
	v_lshlrev_b32_e32 v168, 1, v18
	v_lshlrev_b32_e32 v170, 1, v20
	v_lshlrev_b32_e32 v172, 1, v22
	v_lshlrev_b32_e32 v174, 1, v24
	v_lshlrev_b32_e32 v176, 1, v26
	v_lshlrev_b32_e32 v178, 1, v28
	v_lshlrev_b32_e32 v180, 1, v30
	v_lshlrev_b32_e32 v182, 1, v32
	v_lshlrev_b32_e32 v184, 1, v34
	v_lshlrev_b32_e32 v186, 1, v148
	v_lshlrev_b32_e32 v188, 1, v2
	v_and_b32_e32 v238, 7, v203
	v_lshlrev_b32_e32 v238, 4, v238
	v_lshl_or_b32 v239, v146, 12, v238
	s_add_i32 s22, s87, 1
	v_lshl_or_b32 v238, v146, s22, v238
	s_branch .LBB0_728

; #define LAS __attribute__((address_space(3)))
; __device__ __forceinline__ void phase_attn(const Params& p, int S, int lgS, int B, int* counter, LAS unsigned char* lds) {
;     ...
;     for (int ui = 0; ui < nmine; ++ui) {
;         const int unit = (deal && ui == per) ? (bid_ - nscan) + G_ * (per - 1) : bid_ + ui * G_;
;         const int hq4 = unit & 3, qt = (unit >> 2) & (nqt - 1), bk = unit >> (2 + lgq), kvh = bk & 1, b = bk >> 1, qh = kvh * 4 + hq4;
;         const size_t rowq = (size_t)b * S + qt * 256 + wid * 32 + r32;
;         bf16x8 qr[4];
; #pragma unroll
;         for (int d0 = 0; d0 < 4; ++d0) qr[d0] = *(const bf16x8*)(Z + rowq * 2048 + qh * 64 + d0 * 16 + hi * 8);
;         const bf16_t* ksrc = Z + ((size_t)b * S + skey) * 2048 + 512 + kvh * 64 + spc * 8;
;         const bf16_t* vsrc = VT + (((size_t)(b * 128 + kvh * 64 + skey)) << lgS) + spc * 8;
;         u32x4 kreg0 = *(const u32x4*)ksrc, kreg1 = *(const u32x4*)(ksrc + (size_t)64 * 2048), vreg0 = *(const u32x4*)vsrc, vreg1 = *(const u32x4*)(vsrc + 64);
;         *(LAS u32x4*)(lds + kdst) = kreg0; *(LAS u32x4*)(lds + kdst + 64 * 144) = kreg1; *(LAS u32x4*)(lds + vdst) = vreg0; *(LAS u32x4*)(lds + vdst + 128) = vreg1;
;         __syncthreads();
;         float m_run = 0.f, l_run = 0.f;
;         f32x16 o0 = {0.f, 0.f, 0.f, 0.f, 0.f, 0.f, 0.f, 0.f, 0.f, 0.f, 0.f, 0.f, 0.f, 0.f, 0.f, 0.f}, o1 = o0; const f32x16 zero16 = o0; f32x16 negm = o0;
;         for (int t = 0; t < NT; ++t) {
;             const LAS unsigned char* kb = lds + (t & 1) * BUFB; const LAS unsigned char* vb = kb + KB;
;             if (t + 1 < NT) { const bf16_t* kn = ksrc + (size_t)(t + 1) * 128 * 2048; const bf16_t* vn_ = vsrc + (t + 1) * 128;
;                 kreg0 = *(const u32x4*)kn; kreg1 = *(const u32x4*)(kn + (size_t)64 * 2048); vreg0 = *(const u32x4*)vn_; vreg1 = *(const u32x4*)(vn_ + 64); }
;             f32x16 pp[4] = {negm, negm, negm, negm};
;             const LAS unsigned char* kl = kb + klane; const LAS unsigned char* vl = vb + vlane;
; #pragma unroll
;             for (int d0 = 0; d0 < 4; ++d0)
; #pragma unroll
;                 for (int j = 0; j < 4; ++j) { const bf16x8 a = *(const LAS bf16x8*)(kl + (32 * j * 72 + 16 * d0) * 2); pp[j] = __builtin_amdgcn_mfma_f32_32x32x16_bf16(a, qr[d0], pp[j], 0, 0, 0); }
.LBB0_728:
	v_readlane_b32 s10, v251, 38
	s_cmp_eq_u32 s15, s10
	v_readlane_b32 s16, v251, 34
	s_cselect_b64 s[10:11], -1, 0
	v_readlane_b32 s17, v251, 35
	s_and_b64 s[10:11], s[16:17], s[10:11]
	s_mul_i32 s16, s15, s92
	s_add_i32 s16, s16, s0
	s_and_b64 s[10:11], s[10:11], exec
	s_cselect_b32 s16, s2, s16
	s_lshr_b32 s10, s16, 2
	v_readlane_b32 s11, v251, 18
	s_and_b32 s10, s10, s11
	v_readlane_b32 s11, v251, 13
	s_ashr_i32 s11, s16, s11
	s_ashr_i32 s18, s11, 1
	s_ashr_i32 s19, s18, 31
	s_and_b32 s17, s11, 1
	s_lshl_b64 s[20:21], s[18:19], s87
	s_lshl_b32 s10, s10, 8
	s_add_u32 s10, s10, s3
	s_addc_u32 s11, 0, s14
	s_add_u32 s10, s10, s20
	s_addc_u32 s11, s11, s21
	s_lshl_b32 s16, s16, 6
	v_mov_b32_e32 v1, s11
	v_or_b32_e32 v0, s10, v144
	s_lshl_b32 s19, s17, 8
	s_and_b32 s16, s16, 0xc0
	v_lshlrev_b64 v[0:1], 12, v[0:1]
	s_or_b32 s16, s19, s16
	v_lshl_add_u64 v[0:1], s[8:9], 0, v[0:1]
	s_lshl_b32 s96, s16, 1
	v_lshl_add_u64 v[16:17], v[0:1], 0, s[96:97]
	v_lshl_add_u64 v[0:1], s[20:21], 0, v[146:147]
	v_lshlrev_b64 v[64:65], 12, v[0:1]
	v_lshl_add_u64 v[0:1], s[8:9], 0, v[64:65]
	s_lshl_b32 s19, s17, 6
	s_lshl_b32 s96, s17, 7
	s_lshl_b32 s17, s18, 7
	v_lshl_add_u64 v[0:1], v[0:1], 0, s[96:97]
	v_mov_b32_e32 v189, v201
	s_or_b32 s17, s17, s19
	s_lshl_b64 s[22:23], s[20:21], 12
	s_add_u32 s22, s22, s6
	s_addc_u32 s23, s23, s7
	s_add_u32 s22, s22, 0x13940400
	s_addc_u32 s23, s23, 0
	s_add_u32 s22, s22, s96
	s_addc_u32 s23, s23, 0
	s_sub_u32 s24, s22, 0x40000
	s_subb_u32 s25, s23, 0
	s_add_i32 s30, s87, 1
	s_mov_b32 s28, s17
	s_mov_b32 s29, 0
	s_lshl_b64 s[28:29], s[28:29], s30
	s_add_u32 s28, s28, s6
	s_addc_u32 s29, s29, s7
	s_add_u32 s28, s28, 0x27800200
	s_addc_u32 s29, s29, 0
	v_lshl_add_u64 v[66:67], v[0:1], 0, v[188:189]
	v_add_u32_e32 v0, s17, v146
	s_mov_b32 s17, 0x40000
	v_ashrrev_i32_e32 v1, 31, v0
	v_add_co_u32_e32 v4, vcc, s17, v66
	v_lshlrev_b64 v[0:1], s87, v[0:1]
	s_nop 0
	v_addc_co_u32_e32 v5, vcc, 0, v67, vcc
	v_lshl_add_u64 v[190:191], v[0:1], 1, v[150:151]
	global_load_dwordx4 v[0:3], v[66:67], off offset:1024
	s_nop 0
	global_load_dwordx4 v[4:7], v[4:5], off offset:1024
	s_nop 0
	global_load_dwordx4 v[8:11], v[190:191], off
	global_load_dwordx4 v[12:15], v[190:191], off offset:128
	v_mov_b32_e32 v187, v201
	v_lshl_add_u64 v[16:17], v[16:17], 0, v[186:187]
	global_load_dwordx4 v[112:115], v[16:17], off
	global_load_dwordx4 v[116:119], v[16:17], off offset:32
	global_load_dwordx4 v[120:123], v[16:17], off offset:64
	global_load_dwordx4 v[124:127], v[16:17], off offset:96
	v_add_u32_e32 v68, 0, v145
	v_add_u32_e32 v86, 0, v198
	v_add_u32_e32 v69, 0, v149
	s_mov_b32 s17, 0x80000
	v_add_u32_e32 v93, 0x4800, v223
	v_add_u32_e32 v96, 0x6800, v223
	v_or_b32_e32 v64, s96, v64
	s_mov_b32 s18, 1
	v_lshl_add_u64 v[192:193], v[152:153], 0, v[64:65]
	s_movk_i32 s96, 0x100
	s_waitcnt vmcnt(7)
	ds_write_b128 v68, v[0:3]
	s_waitcnt vmcnt(6)
	ds_write_b128 v68, v[4:7] offset:9216
	s_waitcnt vmcnt(5)
	ds_write2_b64 v69, v[8:9], v[10:11] offset1:2
	s_waitcnt vmcnt(4)
	ds_write2_b64 v69, v[12:13], v[14:15] offset0:16 offset1:18
	s_waitcnt lgkmcnt(0)
	s_barrier
	ds_read_b128 v[0:3], v86
	ds_read_b128 v[70:73], v86 offset:32
	s_waitcnt vmcnt(3) lgkmcnt(1)
	v_mfma_f32_32x32x16_bf16 v[0:15], v[0:3], v[112:115], 0
	ds_read_b128 v[16:19], v86 offset:4608
	ds_read_b128 v[74:77], v86 offset:4640
	ds_read_b128 v[32:35], v86 offset:9216
	ds_read_b128 v[78:81], v86 offset:9248
	ds_read_b128 v[48:51], v86 offset:13824
	ds_read_b128 v[82:85], v86 offset:13856
	s_waitcnt lgkmcnt(5)
	v_mfma_f32_32x32x16_bf16 v[16:31], v[16:19], v[112:115], 0
	s_waitcnt lgkmcnt(3)
	v_mfma_f32_32x32x16_bf16 v[32:47], v[32:35], v[112:115], 0
	s_waitcnt vmcnt(2)
	v_mfma_f32_32x32x16_bf16 v[0:15], v[70:73], v[116:119], v[0:15]
	s_waitcnt lgkmcnt(1)
	v_mfma_f32_32x32x16_bf16 v[48:63], v[48:51], v[112:115], 0
	v_mfma_f32_32x32x16_bf16 v[16:31], v[74:77], v[116:119], v[16:31]
	ds_read_b128 v[70:73], v86 offset:64
	ds_read_b128 v[74:77], v86 offset:96
	v_mfma_f32_32x32x16_bf16 v[32:47], v[78:81], v[116:119], v[32:47]
	s_waitcnt vmcnt(1) lgkmcnt(1)
	v_mfma_f32_32x32x16_bf16 v[0:15], v[70:73], v[120:123], v[0:15]
	ds_read_b128 v[70:73], v86 offset:4672
	ds_read_b128 v[78:81], v86 offset:4704
	v_mfma_f32_32x32x16_bf16 v[48:63], v[82:85], v[116:119], v[48:63]
	s_waitcnt lgkmcnt(1)
	v_mfma_f32_32x32x16_bf16 v[16:31], v[70:73], v[120:123], v[16:31]
	ds_read_b128 v[70:73], v86 offset:9280
	ds_read_b128 v[82:85], v86 offset:9312
	s_waitcnt lgkmcnt(1)
	v_mfma_f32_32x32x16_bf16 v[32:47], v[70:73], v[120:123], v[32:47]
	ds_read_b128 v[70:73], v86 offset:13888
	ds_read_b128 v[86:89], v86 offset:13920
	s_waitcnt lgkmcnt(1)
	v_mfma_f32_32x32x16_bf16 v[48:63], v[70:73], v[120:123], v[48:63]
	v_add_co_u32_e32 v70, vcc, s17, v66
	s_mov_b32 s17, 0xc0000
	s_nop 0
	v_addc_co_u32_e32 v71, vcc, 0, v67, vcc
	v_add_co_u32_e32 v66, vcc, s17, v66
	s_waitcnt vmcnt(0)
	v_mfma_f32_32x32x16_bf16 v[32:47], v[82:85], v[124:127], v[32:47]
	v_addc_co_u32_e32 v67, vcc, 0, v67, vcc
	global_load_dwordx4 v[128:131], v[70:71], off offset:1024
	global_load_dwordx4 v[132:135], v[66:67], off offset:1024
	global_load_dwordx4 v[136:139], v[190:191], off offset:256
	global_load_dwordx4 v[140:143], v[190:191], off offset:384
	s_nop 6
	v_max_f32_e32 v73, v32, v32
	s_waitcnt lgkmcnt(0)
; __device__ __forceinline__ void phase_attn(const Params& p, int S, int lgS, int B, int* counter, LAS unsigned char* lds) {
;     ...
;             float mxa = fmaxf(pp[0][0], pp[1][0]), mxb = fmaxf(pp[2][0], pp[3][0]);
; #pragma unroll
;             for (int r = 1; r < 16; ++r) { mxa = fmaxf(fmaxf(mxa, pp[0][r]), pp[1][r]); mxb = fmaxf(fmaxf(mxb, pp[2][r]), pp[3][r]); }
;             float mx = fmaxf(mxa, mxb);
;             mx = fmaxf(mx, shx(mx, 32, lane));
;             const bool first = (t == 0);
;             if (first || __any(mx > 8.f)) {
;                 const float d = first ? mx : fmaxf(mx, 0.f);
;                 m_run += d;
; #pragma unroll
;                 for (int j = 0; j < 4; ++j)
; #pragma unroll
;                     for (int r = 0; r < 16; ++r) pp[j][r] -= d;
; #pragma unroll
;                 for (int r = 0; r < 16; ++r) negm[r] = -m_run;
;                 if (!first) {
;                     const float alpha = __builtin_amdgcn_exp2f(-d); l_run *= alpha;
;                     if (hi == 0) wsf[r32] = alpha;
;                     LDS_WAIT();
; #pragma unroll
;                     for (int r = 0; r < 16; ++r) { const float f = wsf[crow(r, hi)]; o0[r] *= f; o1[r] *= f; }
;                     LDS_WAIT();
;                 }
;             }
;             float ls = 0.f;
; #pragma unroll
;             for (int j = 0; j < 4; ++j)
; #pragma unroll
;                 for (int r = 0; r < 16; ++r) { pp[j][r] = __builtin_amdgcn_exp2f(pp[j][r]); ls += pp[j][r]; }
;             l_run += ls;
; #pragma unroll
;             for (int j = 0; j < 4; ++j)
; #pragma unroll
;                 for (int kk = 0; kk < 2; ++kk) {
;                     const int ks = 2 * j + kk;
;                     const bf16x8 pa = pack8(pp[j][8 * kk], pp[j][8 * kk + 1], pp[j][8 * kk + 2], pp[j][8 * kk + 3], pp[j][8 * kk + 4], pp[j][8 * kk + 5], pp[j][8 * kk + 6], pp[j][8 * kk + 7]);
;                     const u32x2 v0a = *(const LAS u32x2*)(vl + (16 * ks) * 2), v0b = *(const LAS u32x2*)(vl + (16 * ks + 8) * 2);
;                     const u32x2 v1a = *(const LAS u32x2*)(vl + (32 * 136 + 16 * ks) * 2), v1b = *(const LAS u32x2*)(vl + (32 * 136 + 16 * ks + 8) * 2);
;                     const u32x4 f0 = {v0a.x, v0a.y, v0b.x, v0b.y}, f1 = {v1a.x, v1a.y, v1b.x, v1b.y};
;                     o0 = __builtin_amdgcn_mfma_f32_32x32x16_bf16(pa, __builtin_bit_cast(bf16x8, f0), o0, 0, 0, 0);
	v_mfma_f32_32x32x16_bf16 v[48:63], v[86:89], v[124:127], v[48:63]
	v_mfma_f32_32x32x16_bf16 v[0:15], v[74:77], v[124:127], v[0:15]
	s_nop 10
	v_max_f32_e32 v72, v48, v48
	v_max_f32_e32 v72, v73, v72
	v_max3_f32 v72, v72, v33, v49
	v_max3_f32 v72, v72, v34, v50
	v_max3_f32 v72, v72, v35, v51
	v_max3_f32 v72, v72, v36, v52
	v_max3_f32 v72, v72, v37, v53
	v_mfma_f32_32x32x16_bf16 v[16:31], v[78:81], v[124:127], v[16:31]
	v_max3_f32 v72, v72, v38, v54
	v_max3_f32 v72, v72, v39, v55
	v_max3_f32 v72, v72, v40, v56
	v_max3_f32 v72, v72, v41, v57
	v_max3_f32 v72, v72, v42, v58
	v_max3_f32 v72, v72, v43, v59
	v_max3_f32 v72, v72, v44, v60
	s_nop 4
	v_max3_f32 v74, v0, v16, v1
	v_max3_f32 v73, v74, v17, v2
	v_max3_f32 v73, v73, v18, v3
	v_max3_f32 v73, v73, v19, v4
	v_max3_f32 v73, v73, v20, v5
	v_max3_f32 v73, v73, v21, v6
	v_max3_f32 v73, v73, v22, v7
	v_max3_f32 v73, v73, v23, v8
	v_max3_f32 v73, v73, v24, v9
	v_max3_f32 v73, v73, v25, v10
	v_max3_f32 v73, v73, v26, v11
	v_max3_f32 v73, v73, v27, v12
	v_max3_f32 v73, v73, v28, v13
	v_max3_f32 v72, v72, v45, v61
	v_max3_f32 v73, v73, v29, v14
	v_max3_f32 v72, v72, v46, v62
	v_max3_f32 v73, v73, v30, v15
	v_max3_f32 v72, v72, v47, v63
	v_max3_f32 v72, v73, v31, v72
	ds_bpermute_b32 v73, v209, v72
	s_waitcnt lgkmcnt(0)
	v_max_f32_e32 v66, v73, v73
	v_max_f32_e32 v66, v72, v66
	v_sub_f32_e32 v0, v0, v66
	v_sub_f32_e32 v1, v1, v66
	v_exp_f32_e32 v0, v0
	v_sub_f32_e32 v2, v2, v66
	v_exp_f32_e32 v1, v1
	v_sub_f32_e32 v3, v3, v66
	v_exp_f32_e32 v2, v2
	v_sub_f32_e32 v4, v4, v66
	v_exp_f32_e32 v3, v3
	v_sub_f32_e32 v67, v32, v66
	v_sub_f32_e32 v32, v18, v66
	v_sub_f32_e32 v5, v5, v66
	v_add_f32_e32 v18, 0, v0
	v_exp_f32_e32 v4, v4
	v_sub_f32_e32 v6, v6, v66
	v_add_f32_e32 v18, v1, v18
	v_exp_f32_e32 v5, v5
	v_sub_f32_e32 v7, v7, v66
	v_add_f32_e32 v18, v2, v18
	v_exp_f32_e32 v6, v6
	v_sub_f32_e32 v8, v8, v66
	v_add_f32_e32 v18, v3, v18
	v_exp_f32_e32 v7, v7
	v_sub_f32_e32 v73, v36, v66
	v_sub_f32_e32 v9, v9, v66
	v_add_f32_e32 v18, v4, v18
	v_exp_f32_e32 v36, v8
	v_sub_f32_e32 v74, v37, v66
	v_sub_f32_e32 v10, v10, v66
	v_add_f32_e32 v18, v5, v18
	v_exp_f32_e32 v37, v9
	v_sub_f32_e32 v75, v38, v66
	v_sub_f32_e32 v11, v11, v66
	v_add_f32_e32 v18, v6, v18
	v_exp_f32_e32 v38, v10
	v_sub_f32_e32 v76, v39, v66
	v_sub_f32_e32 v12, v12, v66
	v_add_f32_e32 v18, v7, v18
	v_exp_f32_e32 v39, v11
	v_sub_f32_e32 v13, v13, v66
	v_add_f32_e32 v8, v36, v18
	v_exp_f32_e32 v87, v12
	v_sub_f32_e32 v14, v14, v66
	v_add_f32_e32 v8, v37, v8
	v_exp_f32_e32 v88, v13
	v_sub_f32_e32 v15, v15, v66
	v_add_f32_e32 v8, v38, v8
	v_exp_f32_e32 v89, v14
	v_sub_f32_e32 v16, v16, v66
	v_add_f32_e32 v8, v39, v8
	v_exp_f32_e32 v90, v15
	v_sub_f32_e32 v17, v17, v66
	v_add_f32_e32 v8, v87, v8
	v_exp_f32_e32 v91, v16
	v_sub_f32_e32 v70, v33, v66
	v_sub_f32_e32 v33, v19, v66
	v_add_f32_e32 v8, v88, v8
	v_exp_f32_e32 v92, v17
	v_cvt_pk_bf16_f32 v16, v0, v1
	v_cvt_pk_bf16_f32 v17, v2, v3
	v_cvt_pk_bf16_f32 v18, v4, v5
	v_cvt_pk_bf16_f32 v19, v6, v7
	ds_read_b128 v[0:3], v93
	v_add_f32_e32 v8, v89, v8
	v_exp_f32_e32 v94, v32
	v_add_f32_e32 v8, v90, v8
	v_add_f32_e32 v4, v91, v8
	v_sub_f32_e32 v71, v34, v66
	v_sub_f32_e32 v34, v20, v66
	v_add_f32_e32 v20, v92, v4
	v_sub_f32_e32 v72, v35, v66
	v_sub_f32_e32 v35, v21, v66
	v_sub_f32_e32 v77, v22, v66
	v_sub_f32_e32 v78, v23, v66
	v_sub_f32_e32 v79, v24, v66
	s_waitcnt lgkmcnt(0)
	v_mfma_f32_32x32x16_bf16 v[0:15], v[16:19], v[0:3], 0
	v_add_f32_e32 v24, v94, v20
	ds_read_b128 v[20:23], v96 offset:512
	v_exp_f32_e32 v95, v33
	v_exp_f32_e32 v98, v34
	v_exp_f32_e32 v99, v35
	ds_read_b128 v[32:35], v93 offset:32
	v_cvt_pk_bf16_f32 v36, v36, v37
	v_cvt_pk_bf16_f32 v37, v38, v39
	v_cvt_pk_bf16_f32 v38, v87, v88
	v_cvt_pk_bf16_f32 v39, v89, v90
	v_sub_f32_e32 v80, v25, v66
	v_sub_f32_e32 v81, v26, v66
	v_sub_f32_e32 v82, v27, v66
	v_sub_f32_e32 v83, v28, v66
	v_sub_f32_e32 v84, v29, v66
	v_sub_f32_e32 v85, v30, v66
	v_sub_f32_e32 v86, v31, v66
	v_add_f32_e32 v97, v95, v24
	s_waitcnt lgkmcnt(1)
	v_mfma_f32_32x32x16_bf16 v[16:31], v[16:19], v[20:23], 0
	v_exp_f32_e32 v77, v77
	v_exp_f32_e32 v78, v78
	v_add_f32_e32 v87, v98, v97
	v_add_f32_e32 v87, v99, v87
	v_add_f32_e32 v87, v77, v87
	v_exp_f32_e32 v79, v79
	v_add_f32_e32 v87, v78, v87
	s_waitcnt lgkmcnt(0)
	v_mfma_f32_32x32x16_bf16 v[0:15], v[36:39], v[32:35], v[0:15]
	ds_read_b128 v[32:35], v96 offset:544
	v_exp_f32_e32 v80, v80
	v_exp_f32_e32 v81, v81
	v_exp_f32_e32 v67, v67
	v_exp_f32_e32 v70, v70
	v_exp_f32_e32 v71, v71
	v_exp_f32_e32 v72, v72
	s_waitcnt lgkmcnt(0)
	v_mfma_f32_32x32x16_bf16 v[16:31], v[36:39], v[32:35], v[16:31]
	v_cvt_pk_bf16_f32 v32, v91, v92
	v_cvt_pk_bf16_f32 v33, v94, v95
	v_cvt_pk_bf16_f32 v34, v98, v99
	v_cvt_pk_bf16_f32 v35, v77, v78
	ds_read_b128 v[36:39], v93 offset:64
	v_exp_f32_e32 v78, v82
	v_exp_f32_e32 v82, v83
	s_waitcnt lgkmcnt(0)
	v_mfma_f32_32x32x16_bf16 v[0:15], v[32:35], v[36:39], v[0:15]
	ds_read_b128 v[36:39], v96 offset:576
	v_exp_f32_e32 v83, v84
	v_exp_f32_e32 v84, v85
	v_exp_f32_e32 v85, v86
	v_exp_f32_e32 v73, v73
	v_exp_f32_e32 v74, v74
	v_exp_f32_e32 v75, v75
	s_waitcnt lgkmcnt(0)
	v_mfma_f32_32x32x16_bf16 v[16:31], v[32:35], v[36:39], v[16:31]
	v_cvt_pk_bf16_f32 v32, v79, v80
	v_cvt_pk_bf16_f32 v33, v81, v78
	v_cvt_pk_bf16_f32 v34, v82, v83
	v_cvt_pk_bf16_f32 v35, v84, v85
	ds_read_b128 v[36:39], v93 offset:96
	v_exp_f32_e32 v76, v76
	v_sub_f32_e32 v40, v40, v66
	s_waitcnt lgkmcnt(0)
; #define LAS __attribute__((address_space(3)))
; __device__ __forceinline__ void phase_attn(const Params& p, int S, int lgS, int B, int* counter, LAS unsigned char* lds) {
;     ...
;         for (int t = 0; t < NT; ++t) {
;             const LAS unsigned char* kb = lds + (t & 1) * BUFB; const LAS unsigned char* vb = kb + KB;
;             if (t + 1 < NT) { const bf16_t* kn = ksrc + (size_t)(t + 1) * 128 * 2048; const bf16_t* vn_ = vsrc + (t + 1) * 128;
;                 kreg0 = *(const u32x4*)kn; kreg1 = *(const u32x4*)(kn + (size_t)64 * 2048); vreg0 = *(const u32x4*)vn_; vreg1 = *(const u32x4*)(vn_ + 64); }
;     ...
;             for (int j = 0; j < 4; ++j)
; #pragma unroll
;                 for (int r = 0; r < 16; ++r) { pp[j][r] = __builtin_amdgcn_exp2f(pp[j][r]); ls += pp[j][r]; }
;             l_run += ls;
; #pragma unroll
;             for (int j = 0; j < 4; ++j)
; #pragma unroll
;                 for (int kk = 0; kk < 2; ++kk) {
;                     const int ks = 2 * j + kk;
;                     const bf16x8 pa = pack8(pp[j][8 * kk], pp[j][8 * kk + 1], pp[j][8 * kk + 2], pp[j][8 * kk + 3], pp[j][8 * kk + 4], pp[j][8 * kk + 5], pp[j][8 * kk + 6], pp[j][8 * kk + 7]);
;                     const u32x2 v0a = *(const LAS u32x2*)(vl + (16 * ks) * 2), v0b = *(const LAS u32x2*)(vl + (16 * ks + 8) * 2);
;                     const u32x2 v1a = *(const LAS u32x2*)(vl + (32 * 136 + 16 * ks) * 2), v1b = *(const LAS u32x2*)(vl + (32 * 136 + 16 * ks + 8) * 2);
;                     const u32x4 f0 = {v0a.x, v0a.y, v0b.x, v0b.y}, f1 = {v1a.x, v1a.y, v1b.x, v1b.y};
;                     o0 = __builtin_amdgcn_mfma_f32_32x32x16_bf16(pa, __builtin_bit_cast(bf16x8, f0), o0, 0, 0, 0);
;                     o1 = __builtin_amdgcn_mfma_f32_32x32x16_bf16(pa, __builtin_bit_cast(bf16x8, f1), o1, 0, 0, 0);
;                 }
;             if (t + 1 < NT) { LAS unsigned char* nb = lds + ((t + 1) & 1) * BUFB;
;                 *(LAS u32x4*)(nb + kdst) = kreg0; *(LAS u32x4*)(nb + kdst + 64 * 144) = kreg1; *(LAS u32x4*)(nb + vdst) = vreg0; *(LAS u32x4*)(nb + vdst + 128) = vreg1; }
	v_mfma_f32_32x32x16_bf16 v[0:15], v[32:35], v[36:39], v[0:15]
	ds_read_b128 v[36:39], v96 offset:608
	v_sub_f32_e32 v41, v41, v66
	v_sub_f32_e32 v42, v42, v66
	v_sub_f32_e32 v43, v43, v66
	v_sub_f32_e32 v44, v44, v66
	v_sub_f32_e32 v45, v45, v66
	v_sub_f32_e32 v46, v46, v66
	s_waitcnt lgkmcnt(0)
	v_mfma_f32_32x32x16_bf16 v[16:31], v[32:35], v[36:39], v[16:31]
	v_cvt_pk_bf16_f32 v32, v67, v70
	v_cvt_pk_bf16_f32 v33, v71, v72
	v_cvt_pk_bf16_f32 v34, v73, v74
	v_cvt_pk_bf16_f32 v35, v75, v76
	ds_read_b128 v[36:39], v93 offset:128
	v_sub_f32_e32 v47, v47, v66
	v_exp_f32_e32 v40, v40
	s_waitcnt lgkmcnt(0)
	v_mfma_f32_32x32x16_bf16 v[0:15], v[32:35], v[36:39], v[0:15]
	ds_read_b128 v[36:39], v96 offset:640
	v_exp_f32_e32 v41, v41
	v_exp_f32_e32 v42, v42
	v_exp_f32_e32 v43, v43
	v_exp_f32_e32 v44, v44
	v_exp_f32_e32 v45, v45
	v_exp_f32_e32 v46, v46
	v_exp_f32_e32 v47, v47
	s_waitcnt lgkmcnt(0)
	v_mfma_f32_32x32x16_bf16 v[16:31], v[32:35], v[36:39], v[16:31]
	v_cvt_pk_bf16_f32 v32, v40, v41
	v_cvt_pk_bf16_f32 v33, v42, v43
	v_cvt_pk_bf16_f32 v34, v44, v45
	v_cvt_pk_bf16_f32 v35, v46, v47
	ds_read_b128 v[36:39], v93 offset:160
	v_sub_f32_e32 v48, v48, v66
	v_sub_f32_e32 v49, v49, v66
	v_sub_f32_e32 v50, v50, v66
	v_sub_f32_e32 v51, v51, v66
	v_sub_f32_e32 v52, v52, v66
	v_sub_f32_e32 v53, v53, v66
	v_sub_f32_e32 v54, v54, v66
	v_sub_f32_e32 v55, v55, v66
	s_waitcnt lgkmcnt(0)
	v_mfma_f32_32x32x16_bf16 v[0:15], v[32:35], v[36:39], v[0:15]
	ds_read_b128 v[36:39], v96 offset:672
	v_exp_f32_e32 v48, v48
	v_exp_f32_e32 v49, v49
	v_exp_f32_e32 v50, v50
	v_exp_f32_e32 v51, v51
	v_exp_f32_e32 v52, v52
	v_exp_f32_e32 v53, v53
	v_exp_f32_e32 v54, v54
	v_exp_f32_e32 v55, v55
	v_add_f32_e32 v87, v79, v87
	v_add_f32_e32 v77, v80, v87
	v_add_f32_e32 v77, v81, v77
	v_add_f32_e32 v77, v78, v77
	s_waitcnt lgkmcnt(0)
	v_mfma_f32_32x32x16_bf16 v[16:31], v[32:35], v[36:39], v[16:31]
	v_cvt_pk_bf16_f32 v32, v48, v49
	v_cvt_pk_bf16_f32 v33, v50, v51
	v_cvt_pk_bf16_f32 v34, v52, v53
	v_cvt_pk_bf16_f32 v35, v54, v55
	ds_read_b128 v[36:39], v93 offset:192
	v_add_f32_e32 v77, v82, v77
	v_add_f32_e32 v77, v83, v77
	v_add_f32_e32 v77, v84, v77
	v_add_f32_e32 v77, v85, v77
	v_sub_f32_e32 v56, v56, v66
	v_sub_f32_e32 v57, v57, v66
	v_sub_f32_e32 v58, v58, v66
	v_sub_f32_e32 v59, v59, v66
	v_sub_f32_e32 v60, v60, v66
	v_sub_f32_e32 v61, v61, v66
	v_sub_f32_e32 v62, v62, v66
	v_sub_f32_e32 v63, v63, v66
	v_add_f32_e32 v67, v67, v77
	s_waitcnt lgkmcnt(0)
	v_mfma_f32_32x32x16_bf16 v[0:15], v[32:35], v[36:39], v[0:15]
	ds_read_b128 v[36:39], v96 offset:704
	v_add_f32_e32 v67, v70, v67
	v_exp_f32_e32 v56, v56
	v_exp_f32_e32 v57, v57
	v_exp_f32_e32 v58, v58
	v_exp_f32_e32 v59, v59
	v_exp_f32_e32 v60, v60
	v_exp_f32_e32 v61, v61
	v_exp_f32_e32 v62, v62
	v_exp_f32_e32 v63, v63
	v_add_f32_e32 v67, v71, v67
	v_add_f32_e32 v67, v72, v67
	v_add_f32_e32 v67, v73, v67
	v_add_f32_e32 v67, v74, v67
	s_waitcnt lgkmcnt(0)
	v_mfma_f32_32x32x16_bf16 v[16:31], v[32:35], v[36:39], v[16:31]
	v_cvt_pk_bf16_f32 v32, v56, v57
	v_cvt_pk_bf16_f32 v33, v58, v59
	v_cvt_pk_bf16_f32 v34, v60, v61
	v_cvt_pk_bf16_f32 v35, v62, v63
	ds_read_b128 v[36:39], v93 offset:224
	v_add_f32_e32 v67, v75, v67
	v_add_f32_e32 v67, v76, v67
	v_add_f32_e32 v40, v40, v67
	v_add_f32_e32 v40, v41, v40
	s_waitcnt lgkmcnt(0)
	v_mfma_f32_32x32x16_bf16 v[0:15], v[32:35], v[36:39], v[0:15]
	v_add_f32_e32 v36, v42, v40
	v_add_f32_e32 v40, v43, v36
	ds_read_b128 v[36:39], v96 offset:736
	v_add_f32_e32 v40, v44, v40
	v_add_f32_e32 v40, v45, v40
	v_add_f32_e32 v40, v46, v40
	v_add_f32_e32 v40, v47, v40
	s_waitcnt lgkmcnt(0)
	v_mfma_f32_32x32x16_bf16 v[16:31], v[32:35], v[36:39], v[16:31]
	v_add_f32_e32 v32, v48, v40
	v_add_f32_e32 v32, v49, v32
	v_add_f32_e32 v32, v50, v32
	v_add_f32_e32 v32, v51, v32
	v_add_f32_e32 v32, v52, v32
	v_add_f32_e32 v32, v53, v32
	v_add_f32_e32 v32, v54, v32
	v_add_f32_e32 v32, v55, v32
	v_add_f32_e32 v32, v56, v32
	v_add_f32_e32 v32, v57, v32
	v_add_f32_e32 v32, v58, v32
	v_add_f32_e32 v32, v59, v32
	v_add_f32_e32 v32, v60, v32
	v_add_f32_e32 v32, v61, v32
	v_add_f32_e32 v32, v62, v32
	v_add_f32_e32 v67, v63, v32
	v_pk_add_f32 v[194:195], v[66:67], 0 op_sel_hi:[1,0]
	s_waitcnt vmcnt(3)
	ds_write_b128 v68, v[128:131] offset:35840
	s_waitcnt vmcnt(2)
	ds_write_b128 v68, v[132:135] offset:45056
	s_waitcnt vmcnt(1)
	v_add_u32_e32 v224, 0x8c00, v69
	ds_write2_b64 v224, v[136:137], v[138:139] offset1:2
	s_waitcnt vmcnt(0)
	ds_write2_b64 v224, v[140:141], v[142:143] offset0:16 offset1:18
	v_pk_add_f32 v[32:33], v[194:195], 0 neg_lo:[1,1] neg_hi:[1,1]
	s_waitcnt lgkmcnt(0)
	v_mov_b32_e32 v33, v32
	v_mov_b32_e32 v34, v32
	v_mov_b32_e32 v35, v32
	v_mov_b32_e32 v36, v32
	v_mov_b32_e32 v37, v32
	v_mov_b32_e32 v38, v32
	v_mov_b32_e32 v39, v32
	v_mov_b32_e32 v40, v32
	v_mov_b32_e32 v41, v32
	v_mov_b32_e32 v42, v32
	v_mov_b32_e32 v43, v32
	v_mov_b32_e32 v44, v32
	v_mov_b32_e32 v45, v32
	v_mov_b32_e32 v46, v32
	v_mov_b32_e32 v47, v32
	s_barrier
.LBB0_729:
	s_add_i32 s17, s18, 1
	s_cmp_lt_u32 s17, s93
	s_cselect_b64 s[26:27], -1, 0
	s_cmp_ge_u32 s17, s93
	s_cbranch_scc1 .LBB0_731
	global_load_dwordx4 v[128:131], v239, s[24:25]
	global_load_dwordx4 v[132:135], v239, s[22:23]
	global_load_dwordx4 v[136:139], v238, s[28:29]
	global_load_dwordx4 v[140:143], v238, s[28:29] offset:128

; #define LAS __attribute__((address_space(3)))
; __device__ __forceinline__ void phase_attn(const Params& p, int S, int lgS, int B, int* counter, LAS unsigned char* lds) {
;     ...
;         for (int t = 0; t < NT; ++t) {
;             const LAS unsigned char* kb = lds + (t & 1) * BUFB; const LAS unsigned char* vb = kb + KB;
;             if (t + 1 < NT) { const bf16_t* kn = ksrc + (size_t)(t + 1) * 128 * 2048; const bf16_t* vn_ = vsrc + (t + 1) * 128;
;                 kreg0 = *(const u32x4*)kn; kreg1 = *(const u32x4*)(kn + (size_t)64 * 2048); vreg0 = *(const u32x4*)vn_; vreg1 = *(const u32x4*)(vn_ + 64); }
;     ...
;             if (t + 1 < NT) { LAS unsigned char* nb = lds + ((t + 1) & 1) * BUFB;
;                 *(LAS u32x4*)(nb + kdst) = kreg0; *(LAS u32x4*)(nb + kdst + 64 * 144) = kreg1; *(LAS u32x4*)(nb + vdst) = vreg0; *(LAS u32x4*)(nb + vdst + 128) = vreg1; }
;             __syncthreads();
;         }
.Latt_fast_nowr:
	s_addk_i32 s96, 0x80
	s_mov_b64 s[18:19], 0x80000
	s_add_u32 s22, s22, 0x80000
	s_addc_u32 s23, s23, 0
	s_add_u32 s24, s24, 0x80000
	s_addc_u32 s25, s25, 0
	s_add_u32 s28, s28, 0x100
	s_addc_u32 s29, s29, 0
	s_cmp_eq_u32 s93, s17
	s_waitcnt lgkmcnt(0)
	s_barrier
	s_cbranch_scc1 .LBB0_739
	s_mov_b32 s18, s17
	s_branch .LBB0_729

; #define LAS __attribute__((address_space(3)))
; __device__ __forceinline__ void phase_attn(const Params& p, int S, int lgS, int B, int* counter, LAS unsigned char* lds) {
;     ...
;         for (int t = 0; t < NT; ++t) {
;             const LAS unsigned char* kb = lds + (t & 1) * BUFB; const LAS unsigned char* vb = kb + KB;
;             if (t + 1 < NT) { const bf16_t* kn = ksrc + (size_t)(t + 1) * 128 * 2048; const bf16_t* vn_ = vsrc + (t + 1) * 128;
;                 kreg0 = *(const u32x4*)kn; kreg1 = *(const u32x4*)(kn + (size_t)64 * 2048); vreg0 = *(const u32x4*)vn_; vreg1 = *(const u32x4*)(vn_ + 64); }
;     ...
;             float ls = 0.f;
; #pragma unroll
;             for (int j = 0; j < 4; ++j)
; #pragma unroll
;                 for (int r = 0; r < 16; ++r) { pp[j][r] = __builtin_amdgcn_exp2f(pp[j][r]); ls += pp[j][r]; }
;             l_run += ls;
.LBB0_737:
	v_add_f32_e32 v96, 0, v96
	v_add_f32_e32 v96, v97, v96
	v_add_f32_e32 v96, v98, v96
	v_add_f32_e32 v96, v99, v96
	v_add_f32_e32 v96, v100, v96
	v_add_f32_e32 v96, v101, v96
	v_add_f32_e32 v96, v102, v96
	v_add_f32_e32 v96, v103, v96
	v_add_f32_e32 v96, v104, v96
	v_add_f32_e32 v96, v105, v96
	v_add_f32_e32 v96, v106, v96
	v_add_f32_e32 v96, v107, v96
	v_add_f32_e32 v96, v108, v96
	v_add_f32_e32 v96, v109, v96
	v_add_f32_e32 v96, v110, v96
	v_add_f32_e32 v96, v111, v96
	v_add_f32_e32 v80, v80, v96
	v_add_f32_e32 v80, v81, v80
	v_add_f32_e32 v80, v82, v80
	v_add_f32_e32 v80, v83, v80
	v_add_f32_e32 v80, v84, v80
	v_add_f32_e32 v80, v85, v80
	v_add_f32_e32 v80, v86, v80
	v_add_f32_e32 v80, v87, v80
	v_add_f32_e32 v80, v88, v80
	v_add_f32_e32 v80, v89, v80
	v_add_f32_e32 v80, v90, v80
	v_add_f32_e32 v80, v91, v80
	v_add_f32_e32 v80, v92, v80
	v_add_f32_e32 v80, v93, v80
	v_add_f32_e32 v80, v94, v80
	v_add_f32_e32 v80, v95, v80
	v_add_f32_e32 v64, v64, v80
	v_add_f32_e32 v64, v65, v64
	v_add_f32_e32 v64, v66, v64
	v_add_f32_e32 v64, v67, v64
	v_add_f32_e32 v64, v68, v64
	v_add_f32_e32 v64, v69, v64
	v_add_f32_e32 v64, v70, v64
	v_add_f32_e32 v64, v71, v64
	v_add_f32_e32 v64, v72, v64
	v_add_f32_e32 v64, v73, v64
	v_add_f32_e32 v64, v74, v64
	v_add_f32_e32 v64, v75, v64
	v_add_f32_e32 v64, v76, v64
	v_add_f32_e32 v64, v77, v64
	v_add_f32_e32 v64, v78, v64
	v_add_f32_e32 v64, v79, v64
	v_add_f32_e32 v48, v48, v64
	v_add_f32_e32 v48, v49, v48
	v_add_f32_e32 v48, v50, v48
	v_add_f32_e32 v48, v51, v48
	v_add_f32_e32 v48, v52, v48
	v_add_f32_e32 v48, v53, v48
	v_add_f32_e32 v48, v54, v48
	v_add_f32_e32 v48, v55, v48
	v_add_f32_e32 v48, v56, v48
	v_add_f32_e32 v48, v57, v48
	v_add_f32_e32 v48, v58, v48
	v_add_f32_e32 v48, v59, v48
	v_add_f32_e32 v48, v60, v48
	v_add_f32_e32 v48, v61, v48
	v_add_f32_e32 v48, v62, v48
	v_add_f32_e32 v48, v63, v48
	s_addk_i32 s96, 0x80
	s_mov_b64 s[18:19], 0x80000
	v_add_f32_e32 v195, v195, v48
	s_add_u32 s22, s22, 0x80000
	s_addc_u32 s23, s23, 0
	s_add_u32 s24, s24, 0x80000
	s_addc_u32 s25, s25, 0
	s_add_u32 s28, s28, 0x100
	s_addc_u32 s29, s29, 0
	s_cmp_eq_u32 s93, s17
	s_waitcnt lgkmcnt(0)
	s_barrier
	s_cbranch_scc1 .LBB0_739
	s_mov_b32 s18, s17
	s_branch .LBB0_729
